# final stack + attention: the three loop-top vmcnt waits relaxed to vmcnt(4) (no wait for the previous unit's store acknowledgements), one full wait before the loop
# baseline (speedup 1.0000x reference)
.LBB0_313:
	s_mov_b32 s100, 0x12000
	s_and_b64 vcc, exec, s[8:9]
	s_cbranch_vccnz .LBB0_438
	v_and_b32_e32 v3, 64, v209
	v_xor_b32_e32 v2, 1, v209
	v_add_u32_e32 v3, 64, v3
	v_cmp_lt_i32_e32 vcc, v2, v3
	v_lshlrev_b32_e32 v0, 2, v73
	v_readlane_b32 s58, v253, 8
	v_cndmask_b32_e32 v2, v209, v2, vcc
	v_lshlrev_b32_e32 v174, 2, v2
	v_xor_b32_e32 v2, 2, v209
	v_cmp_lt_i32_e32 vcc, v2, v3
	v_readlane_b32 s12, v253, 23
	v_add_u32_e32 v173, s58, v0
	v_cndmask_b32_e32 v2, v209, v2, vcc
	v_lshlrev_b32_e32 v175, 2, v2
	v_xor_b32_e32 v2, 4, v209
	v_and_b32_e32 v0, 0x1fc, v0
	s_and_b64 s[8:9], s[92:93], exec
	v_readlane_b32 s13, v253, 24
	v_cmp_lt_i32_e32 vcc, v2, v3
	v_add_u32_e32 v69, 0, v0
	v_xor_b32_e32 v0, 16, v209
	s_cselect_b32 s0, 5, 3
	s_and_b64 s[8:9], s[12:13], exec
	v_cndmask_b32_e32 v2, v209, v2, vcc
	v_cmp_lt_i32_e32 vcc, v0, v3
	s_cselect_b32 s47, 7, s0
	s_add_i32 s56, s56, -1
	s_lshl_b32 s24, s28, 4
	v_cndmask_b32_e32 v0, v209, v0, vcc
	s_and_b64 s[8:9], s[92:93], exec
	v_lshlrev_b32_e32 v177, 2, v0
	v_xor_b32_e32 v0, 32, v209
	s_cselect_b32 s0, 2, 4
	s_and_b64 s[8:9], s[12:13], exec
	v_cmp_lt_i32_e32 vcc, v0, v3
	v_add_u32_e32 v3, 0x400, v73
	s_cselect_b32 s57, 0, s0
	v_cndmask_b32_e32 v0, v209, v0, vcc
	s_and_b64 s[8:9], s[92:93], exec
	v_ashrrev_i32_e32 v180, 3, v3
	v_add_u32_e32 v3, 0x600, v73
	v_lshlrev_b32_e32 v178, 2, v0
	s_cselect_b32 s0, 12, 10
	s_and_b64 s[8:9], s[12:13], exec
	v_add_u32_e32 v0, 0x200, v73
	v_ashrrev_i32_e32 v181, 3, v3
	v_lshlrev_b32_e32 v3, 1, v73
	s_cselect_b32 s99, 14, s0
	v_ashrrev_i32_e32 v179, 3, v0
	v_and_b32_e32 v182, 0xfe, v3
	v_ashrrev_i32_e32 v3, 4, v73
	v_ashrrev_i32_e32 v0, 4, v0
	s_ashr_i32 s0, s24, 31
	v_and_b32_e32 v124, -8, v3
	v_and_b32_e32 v126, -8, v0
	v_mov_b32_e32 v121, s0
	s_movk_i32 s0, 0x210
	v_lshlrev_b32_e32 v128, 2, v74
	v_mul_lo_u32 v78, v124, s0
	v_mul_lo_u32 v79, v126, s0
	s_add_i32 s29, s28, 2
	s_add_i32 s35, s28, 4
	s_add_i32 s34, s28, 6
	s_add_i32 s0, s28, 8
	v_mov_b32_e32 v71, v1
	v_sub_u32_e32 v0, v72, v128
	s_add_i32 s40, s24, 16
	s_lshl_b32 s41, s29, 4
	s_add_i32 s42, s24, 48
	s_lshl_b32 s43, s35, 4
	s_add_i32 s49, s24, 0x50
	s_lshl_b32 s52, s34, 4
	s_add_i32 s48, s24, 0x70
	s_lshl_b32 s53, s0, 4
	v_or_b32_e32 v120, s24, v72
	v_lshl_add_u64 v[122:123], s[10:11], 0, v[70:71]
	v_add_u32_e32 v70, 0x80, v0
	s_movk_i32 s8, 0x90
	v_or_b32_e32 v81, s40, v72
	v_or_b32_e32 v82, s41, v72
	v_or_b32_e32 v83, s42, v72
	v_or_b32_e32 v84, s43, v72
	v_or_b32_e32 v85, s49, v72
	v_or_b32_e32 v86, s52, v72
	v_or_b32_e32 v87, s48, v72
	v_or_b32_e32 v88, s53, v72
	s_movk_i32 s55, 0x81
	v_lshl_add_u32 v3, v74, 4, 0
	v_cmp_eq_u32_e32 vcc, 0, v74
	v_mul_lo_u32 v74, v129, s8
	v_mul_lo_u32 v75, v179, s8
	v_mul_lo_u32 v76, v180, s8
	v_mul_lo_u32 v77, v181, s8
	v_mul_lo_u32 v80, v120, s8
	v_mul_lo_u32 v81, v81, s8
	v_mul_lo_u32 v82, v82, s8
	v_mul_lo_u32 v83, v83, s8
	v_mul_lo_u32 v84, v84, s8
	v_mul_lo_u32 v85, v85, s8
	v_mul_lo_u32 v86, v86, s8
	v_mul_lo_u32 v87, v87, s8
	v_mul_lo_u32 v88, v88, s8
	v_cmp_gt_u32_e64 s[8:9], s55, v70
	v_lshl_add_u32 v183, v70, 2, s58
	v_add_u32_e32 v70, 0x7f, v0
	v_cmp_gt_u32_e64 s[10:11], s55, v70
	v_lshl_add_u32 v184, v70, 2, s58
	v_add_u32_e32 v70, 0x7e, v0
	v_cmp_gt_u32_e64 s[12:13], s55, v70
	v_lshl_add_u32 v185, v70, 2, s58
	v_add_u32_e32 v70, 0x7d, v0
	v_lshl_add_u32 v187, v0, 2, s58
	v_cmp_lt_i32_e64 s[16:17], -1, v0
	v_cmp_lt_i32_e64 s[18:19], 0, v0
	v_cmp_lt_i32_e64 s[20:21], 1, v0
	v_cmp_lt_i32_e64 s[22:23], 2, v0
	v_or_b32_e32 v0, s24, v128
	s_movk_i32 s54, 0x7f
	s_and_b64 s[38:39], s[88:89], vcc
	v_cmp_gt_u32_e64 s[14:15], s55, v70
	v_lshl_add_u32 v186, v70, 2, s58
	v_cmp_lt_i32_e32 vcc, s54, v0
	v_or_b32_e32 v70, 1, v128
	s_and_b64 s[24:25], s[8:9], vcc
	v_sub_u32_e32 v89, v72, v70
	v_writelane_b32 v254, s24, 39
	v_add_u32_e32 v90, 0x80, v89
	s_movk_i32 s59, 0x7e
	v_lshl_add_u32 v191, v89, 2, s58
	v_or_b32_e32 v89, 2, v128
	v_writelane_b32 v254, s25, 40
	v_cmp_gt_u32_e32 vcc, s55, v90
	v_cmp_lt_i32_e64 s[24:25], s59, v0
	v_sub_u32_e32 v90, v72, v89
	s_and_b64 s[24:25], vcc, s[24:25]
	v_add_u32_e32 v91, 0x80, v90
	v_writelane_b32 v254, s24, 41
	v_cmp_gt_u32_e32 vcc, s55, v91
	v_or_b32_e32 v91, 2, v0
	v_writelane_b32 v254, s25, 42
	v_cmp_lt_i32_e64 s[24:25], s54, v91
	v_lshl_add_u32 v192, v90, 2, s58
	v_or_b32_e32 v90, 3, v128
	s_and_b64 s[24:25], vcc, s[24:25]
	v_sub_u32_e32 v91, v72, v90
	v_writelane_b32 v254, s24, 35
	v_add_u32_e32 v92, 0x80, v91
	v_or_b32_e32 v0, 3, v0
	v_writelane_b32 v254, s25, 36
	v_cmp_gt_u32_e32 vcc, s55, v92
	v_cmp_lt_i32_e64 s[24:25], s54, v0
	s_and_b64 s[24:25], vcc, s[24:25]
	v_or_b32_e32 v0, s40, v128
	v_writelane_b32 v254, s24, 25
	v_lshlrev_b32_e32 v176, 2, v2
	v_lshlrev_b32_e32 v2, 4, v73
	v_writelane_b32 v254, s25, 26
	v_or_b32_e32 v73, -16, v73
	v_cmp_lt_i32_e64 s[24:25], s54, v0
	v_lshl_add_u32 v193, v91, 2, s58
	v_sub_u32_e32 v91, v73, v128
	v_writelane_b32 v254, s24, 33
	v_lshl_add_u32 v194, v91, 2, s58
	v_sub_u32_e32 v91, v73, v70
	v_writelane_b32 v254, s25, 34
	v_cmp_lt_i32_e64 s[24:25], s59, v0
	v_lshl_add_u32 v195, v91, 2, s58
	v_or_b32_e32 v91, 2, v0
	v_writelane_b32 v254, s24, 27
	v_or_b32_e32 v0, 3, v0
	v_or_b32_e32 v93, 0xffffff80, v72
	v_writelane_b32 v254, s25, 28
	v_cmp_lt_i32_e64 s[24:25], s54, v91
	v_sub_u32_e32 v91, v73, v89
	v_lshl_add_u32 v196, v91, 2, s58
	v_writelane_b32 v254, s24, 43
	v_sub_u32_e32 v94, v93, v128
	v_add_u32_e32 v95, 0x80, v94
	v_writelane_b32 v254, s25, 44
	v_cmp_lt_i32_e64 s[24:25], s54, v0
	v_sub_u32_e32 v0, v73, v90
	v_lshl_add_u32 v197, v0, 2, s58
	v_writelane_b32 v254, s24, 37
	v_or_b32_e32 v0, s41, v128
	v_or_b32_e32 v73, 0xffffffe0, v72
	v_writelane_b32 v254, s25, 38
	v_cmp_lt_i32_e64 s[24:25], s54, v0
	v_sub_u32_e32 v91, v73, v128
	v_lshl_add_u32 v198, v91, 2, s58
	v_writelane_b32 v254, s24, 29
	v_sub_u32_e32 v91, v73, v70
	v_lshl_add_u32 v200, v91, 2, s58
	v_writelane_b32 v254, s25, 30
	v_cmp_lt_i32_e64 s[24:25], s59, v0
	v_or_b32_e32 v91, 2, v0
	v_or_b32_e32 v0, 3, v0
	v_writelane_b32 v254, s24, 31
	v_or_b32_e32 v92, s53, v128
	v_cmp_gt_u32_e32 vcc, s55, v95
	v_writelane_b32 v254, s25, 32
	v_cmp_lt_i32_e64 s[24:25], s54, v91
	v_sub_u32_e32 v91, v73, v89
	v_lshl_add_u32 v201, v91, 2, s58
	v_writelane_b32 v254, s24, 45
	v_sub_u32_e32 v95, v93, v70
	v_cmp_lt_i32_e64 s[64:65], s54, v92
	v_writelane_b32 v254, s25, 46
	v_cmp_lt_i32_e64 s[24:25], s54, v0
	v_sub_u32_e32 v0, v73, v90
	v_lshl_add_u32 v202, v0, 2, s58
	v_writelane_b32 v254, s24, 47
	v_or_b32_e32 v0, s42, v128
	v_or_b32_e32 v73, 0xffffffd0, v72
	v_writelane_b32 v254, s25, 48
	v_cmp_lt_i32_e64 s[24:25], s54, v0
	v_sub_u32_e32 v91, v73, v128
	v_lshl_add_u32 v203, v91, 2, s58
	v_writelane_b32 v254, s24, 49
	v_sub_u32_e32 v91, v73, v70
	v_lshl_add_u32 v210, v91, 2, s58
	v_writelane_b32 v254, s25, 50
	v_cmp_lt_i32_e64 s[24:25], s59, v0
	v_or_b32_e32 v91, 2, v0
	v_or_b32_e32 v0, 3, v0
	v_writelane_b32 v254, s24, 51
	v_add_u32_e32 v96, 0x80, v95
	s_and_b64 s[40:41], vcc, s[64:65]
	v_writelane_b32 v254, s25, 52
	v_cmp_lt_i32_e64 s[24:25], s54, v91
	v_sub_u32_e32 v91, v73, v89
	v_lshl_add_u32 v211, v91, 2, s58
	v_writelane_b32 v254, s24, 53
	v_cmp_gt_u32_e32 vcc, s55, v96
	v_sub_u32_e32 v96, v93, v89
	v_writelane_b32 v254, s25, 54
	v_cmp_lt_i32_e64 s[24:25], s54, v0
	v_sub_u32_e32 v0, v73, v90
	v_lshl_add_u32 v212, v0, 2, s58
	v_writelane_b32 v254, s24, 55
	v_or_b32_e32 v0, s43, v128
	v_or_b32_e32 v73, 0xffffffc0, v72
	v_writelane_b32 v254, s25, 56
	v_cmp_lt_i32_e64 s[24:25], s54, v0
	v_sub_u32_e32 v91, v73, v128
	v_lshl_add_u32 v213, v91, 2, s58
	v_writelane_b32 v254, s24, 57
	v_sub_u32_e32 v91, v73, v70
	v_lshl_add_u32 v214, v91, 2, s58
	v_writelane_b32 v254, s25, 58
	v_cmp_lt_i32_e64 s[24:25], s59, v0
	v_or_b32_e32 v91, 2, v0
	v_or_b32_e32 v0, 3, v0
	v_writelane_b32 v254, s24, 59
	v_cmp_lt_i32_e64 s[64:65], s59, v92
	v_add_u32_e32 v97, 0x80, v96
	v_writelane_b32 v254, s25, 60
	v_cmp_lt_i32_e64 s[24:25], s54, v91
	v_sub_u32_e32 v91, v73, v89
	v_lshl_add_u32 v215, v91, 2, s58
	v_writelane_b32 v254, s24, 61
	s_and_b64 s[42:43], vcc, s[64:65]
	v_cmp_gt_u32_e32 vcc, s55, v97
	v_writelane_b32 v254, s25, 62
	v_cmp_lt_i32_e64 s[24:25], s54, v0
	v_sub_u32_e32 v0, v73, v90
	v_or_b32_e32 v73, 0xffffffb0, v72
	v_sub_u32_e32 v91, v73, v128
	v_or_b32_e32 v97, 2, v92
	v_sub_u32_e32 v93, v93, v90
	v_writelane_b32 v254, s24, 63
	v_lshl_add_u32 v216, v0, 2, s58
	v_or_b32_e32 v0, s49, v128
	v_lshl_add_u32 v217, v91, 2, s58
	v_sub_u32_e32 v91, v73, v70
	v_cmp_lt_i32_e64 s[64:65], s54, v97
	v_add_u32_e32 v97, 0x80, v93
	v_or_b32_e32 v92, 3, v92
	v_writelane_b32 v255, s25, 0
	v_cmp_lt_i32_e64 s[24:25], s54, v0
	v_cmp_lt_i32_e64 s[60:61], s59, v0
	v_lshl_add_u32 v218, v91, 2, s58
	v_or_b32_e32 v91, 2, v0
	v_or_b32_e32 v0, 3, v0
	s_and_b64 s[88:89], vcc, s[64:65]
	v_cmp_gt_u32_e32 vcc, s55, v97
	v_cmp_lt_i32_e64 s[64:65], s54, v92
	s_and_b64 s[92:93], vcc, s[64:65]
	v_cmp_lt_i32_e64 s[64:65], s54, v0
	v_sub_u32_e32 v0, v73, v90
	v_cmp_lt_i32_e64 s[62:63], s54, v91
	v_sub_u32_e32 v91, v73, v89
	v_lshl_add_u32 v220, v0, 2, s58
	v_or_b32_e32 v0, 0xffffffa0, v72
	v_lshl_add_u32 v219, v91, 2, s58
	v_or_b32_e32 v91, s52, v128
	v_sub_u32_e32 v99, v0, v70
	v_lshl_add_u32 v222, v99, 2, s58
	v_or_b32_e32 v99, 2, v91
	v_sub_u32_e32 v97, v0, v128
	v_cmp_lt_i32_e64 s[70:71], s54, v99
	v_sub_u32_e32 v99, v0, v89
	v_sub_u32_e32 v0, v0, v90
	v_writelane_b32 v255, s24, 1
	v_lshl_add_u32 v224, v0, 2, s58
	v_or_b32_e32 v0, 0xffffff90, v72
	v_and_b32_e32 v2, 0x70, v2
	v_sub_u32_e32 v71, v3, v68
	v_writelane_b32 v255, s25, 2
	v_or_b32_e32 v73, s48, v128
	v_lshl_add_u32 v223, v99, 2, s58
	v_sub_u32_e32 v99, v0, v128
	v_sub_u32_e32 v70, v0, v70
	v_sub_u32_e32 v89, v0, v89
	v_sub_u32_e32 v0, v0, v90
	v_readlane_b32 s24, v254, 12
	v_add_u32_e32 v2, 0, v2
	v_lshl_add_u32 v92, s28, 5, v71
	v_cmp_lt_i32_e64 s[66:67], s54, v91
	v_lshl_add_u32 v221, v97, 2, s58
	v_lshl_add_u32 v97, s29, 5, v71
	v_lshl_add_u32 v98, s35, 5, v71
	v_cmp_lt_i32_e64 s[68:69], s59, v91
	v_lshl_add_u32 v100, s34, 5, v71
	v_lshl_add_u32 v71, s0, 5, v71
	v_or_b32_e32 v91, 3, v91
	v_lshl_add_u32 v226, v70, 2, s58
	v_or_b32_e32 v70, 2, v73
	v_lshl_add_u32 v227, v89, 2, s58
	v_or_b32_e32 v89, 3, v73
	v_lshl_add_u32 v228, v0, 2, s58
	v_mul_u32_u24_e32 v72, 0x210, v72
	v_lshlrev_b32_e32 v0, 1, v68
	v_readlane_b32 s25, v254, 13
	v_ashrrev_i32_e32 v125, 31, v124
	v_ashrrev_i32_e32 v127, 31, v126
	v_add_u32_e32 v188, -4, v187
	v_add_u32_e32 v189, -8, v187
	v_add_u32_e32 v190, -12, v187
	v_lshl_add_u32 v225, v99, 2, s58
	v_lshl_add_u32 v229, v94, 2, s58
	v_lshl_add_u32 v230, v95, 2, s58
	v_lshl_add_u32 v231, v96, 2, s58
	v_lshl_add_u32 v232, v93, 2, s58
	v_lshl_add_u64 v[132:133], s[24:25], 0, v[0:1]
	v_add_u32_e32 v233, v2, v74
	v_add_u32_e32 v234, v2, v75
	v_add_u32_e32 v235, v2, v76
	v_add_u32_e32 v236, v2, v77
	v_add_u32_e32 v237, v69, v78
	v_add_u32_e32 v238, v69, v79
	v_add_u32_e32 v239, v3, v80
	v_add_u32_e32 v240, v3, v81
	v_add_u32_e32 v241, v3, v82
	v_add_u32_e32 v242, v3, v83
	v_add_u32_e32 v243, v3, v84
	v_add_u32_e32 v244, v3, v85
	v_add_u32_e32 v245, v3, v86
	v_add_u32_e32 v246, v3, v87
	v_add_u32_e32 v247, v3, v88
	v_add_u32_e32 v248, v92, v72
	v_add_u32_e32 v249, v97, v72
	v_add_u32_e32 v250, v98, v72
	v_add_u32_e32 v251, v100, v72
	v_add_u32_e32 v206, v71, v72
	v_readlane_b32 s58, v252, 47
	v_cmp_lt_i32_e64 s[72:73], s54, v91
	v_cmp_lt_i32_e64 s[74:75], s54, v73
	v_cmp_lt_i32_e64 s[76:77], s59, v73
	v_cmp_lt_i32_e64 s[78:79], s54, v70
	v_cmp_lt_i32_e64 s[80:81], s54, v89
	s_waitcnt vmcnt(0)
	s_branch .LBB0_316

.LBB0_316:
	s_and_saveexec_b64 s[24:25], s[6:7]
	s_cbranch_execz .LBB0_318
	s_waitcnt vmcnt(4)
	v_mul_f32_e32 v0, 0x3fb8aa3b, v172
	ds_write_b32 v173, v0
.LBB0_318:
	s_or_b64 exec, exec, s[24:25]
	s_waitcnt vmcnt(4)
	v_lshlrev_b32_e32 v78, 16, v32
	v_and_b32_e32 v79, 0xffff0000, v32
	v_lshlrev_b32_e32 v74, 16, v33
	v_and_b32_e32 v75, 0xffff0000, v33
	v_pk_mul_f32 v[80:81], v[78:79], v[78:79]
	v_pk_mul_f32 v[76:77], v[74:75], v[74:75]
	v_add_f32_e32 v0, v80, v81
	v_lshlrev_b32_e32 v70, 16, v34
	v_and_b32_e32 v71, 0xffff0000, v34
	v_add_f32_e32 v0, v76, v0
	v_pk_mul_f32 v[72:73], v[70:71], v[70:71]
	v_add_f32_e32 v0, v77, v0
	v_lshlrev_b32_e32 v2, 16, v35
	v_and_b32_e32 v3, 0xffff0000, v35
	v_add_f32_e32 v0, v72, v0
	v_pk_mul_f32 v[68:69], v[2:3], v[2:3]
	v_add_f32_e32 v0, v73, v0
	v_add_f32_e32 v0, v68, v0
	v_add_f32_e32 v0, v69, v0
	ds_bpermute_b32 v68, v174, v0
	v_lshlrev_b32_e32 v86, 16, v28
	v_and_b32_e32 v87, 0xffff0000, v28
	v_lshlrev_b32_e32 v102, 16, v36
	v_and_b32_e32 v103, 0xffff0000, v36
	s_waitcnt lgkmcnt(0)
	v_add_f32_e32 v0, v0, v68
	ds_bpermute_b32 v68, v175, v0
	v_lshlrev_b32_e32 v82, 16, v29
	v_and_b32_e32 v83, 0xffff0000, v29
	v_pk_mul_f32 v[88:89], v[86:87], v[86:87]
	v_lshlrev_b32_e32 v98, 16, v37
	s_waitcnt lgkmcnt(0)
	v_add_f32_e32 v0, v0, v68
	ds_bpermute_b32 v68, v176, v0
	v_and_b32_e32 v99, 0xffff0000, v37
	v_pk_mul_f32 v[104:105], v[102:103], v[102:103]
	v_pk_mul_f32 v[84:85], v[82:83], v[82:83]
	v_pk_mul_f32 v[100:101], v[98:99], v[98:99]
	v_mov_b32_e32 v106, v104
	v_mov_b32_e32 v107, v88
	v_mov_b32_e32 v88, v105
	s_waitcnt lgkmcnt(0)
	v_add_f32_e32 v0, v0, v68
	v_lshlrev_b32_e32 v76, 16, v30
	v_and_b32_e32 v77, 0xffff0000, v30
	v_lshlrev_b32_e32 v94, 16, v38
	v_and_b32_e32 v95, 0xffff0000, v38
	v_pk_add_f32 v[88:89], v[106:107], v[88:89]
	v_mov_b32_e32 v104, v100
	v_mov_b32_e32 v105, v84
	v_fmamk_f32 v0, v0, 0x3c800000, v205
	v_pk_mul_f32 v[80:81], v[76:77], v[76:77]
	v_pk_mul_f32 v[96:97], v[94:95], v[94:95]
	v_pk_add_f32 v[88:89], v[104:105], v[88:89]
	v_mov_b32_e32 v84, v101
	v_lshlrev_b32_e32 v72, 16, v31
	v_mul_f32_e32 v68, 0x4b800000, v0
	v_cmp_gt_f32_e32 vcc, s83, v0
	v_and_b32_e32 v73, 0xffff0000, v31
	v_lshlrev_b32_e32 v90, 16, v39
	v_and_b32_e32 v91, 0xffff0000, v39
	v_pk_add_f32 v[84:85], v[84:85], v[88:89]
	v_mov_b32_e32 v88, v96
	v_mov_b32_e32 v89, v80
	v_cndmask_b32_e32 v0, v0, v68, vcc
	v_pk_mul_f32 v[68:69], v[72:73], v[72:73]
	v_pk_mul_f32 v[92:93], v[90:91], v[90:91]
	v_pk_add_f32 v[84:85], v[88:89], v[84:85]
	v_mov_b32_e32 v80, v97
	v_pk_add_f32 v[80:81], v[80:81], v[84:85]
	v_mov_b32_e32 v84, v92
	v_mov_b32_e32 v85, v68
	v_pk_add_f32 v[80:81], v[84:85], v[80:81]
	v_mov_b32_e32 v68, v93
	v_pk_add_f32 v[68:69], v[68:69], v[80:81]
	ds_bpermute_b32 v81, v174, v69
	ds_bpermute_b32 v80, v174, v68
	v_rsq_f32_e32 v0, v0
	s_mov_b32 s0, 0x358637bd
	s_mov_b32 s24, 0x3c800000
	v_lshlrev_b32_e32 v96, 16, v40
	v_mul_f32_e32 v84, 0x45800000, v0
	s_waitcnt lgkmcnt(0)
	v_pk_add_f32 v[80:81], v[68:69], v[80:81]
	v_cndmask_b32_e32 v0, v0, v84, vcc
	ds_bpermute_b32 v85, v175, v81
	ds_bpermute_b32 v84, v175, v80
	v_pk_mul_f32 v[74:75], v[0:1], v[74:75] op_sel_hi:[0,1]
	v_pk_mul_f32 v[78:79], v[0:1], v[78:79] op_sel_hi:[0,1]
	v_pk_mul_f32 v[74:75], v[10:11], v[74:75]
	v_pk_mul_f32 v[78:79], v[8:9], v[78:79]
	v_cvt_pk_bf16_f32 v69, v74, v75
	s_waitcnt lgkmcnt(0)
	v_pk_add_f32 v[74:75], v[80:81], v[84:85]
	v_cvt_pk_bf16_f32 v68, v78, v79
	ds_bpermute_b32 v79, v176, v75
	ds_bpermute_b32 v78, v176, v74
	v_mov_b64_e32 v[84:85], s[0:1]
	v_pk_mul_f32 v[70:71], v[0:1], v[70:71] op_sel_hi:[0,1]
	v_pk_mul_f32 v[2:3], v[0:1], v[2:3] op_sel_hi:[0,1]
	v_pk_mul_f32 v[70:71], v[4:5], v[70:71]
	s_waitcnt lgkmcnt(0)
	v_pk_add_f32 v[74:75], v[74:75], v[78:79]
	v_pk_mul_f32 v[2:3], v[6:7], v[2:3]
	v_pk_fma_f32 v[74:75], v[74:75], s[24:25], v[84:85] op_sel_hi:[1,0,0]
	v_cvt_pk_bf16_f32 v70, v70, v71
	v_mul_f32_e32 v0, 0x4b800000, v75
	v_cmp_gt_f32_e32 vcc, s83, v75
	v_cvt_pk_bf16_f32 v71, v2, v3
	ds_write_b128 v233, v[68:71]
	v_cndmask_b32_e32 v0, v75, v0, vcc
	v_rsq_f32_e32 v0, v0
	s_waitcnt vmcnt(4)
	v_and_b32_e32 v75, 0xffff0000, v64
	v_lshlrev_b32_e32 v92, 16, v41
	v_and_b32_e32 v93, 0xffff0000, v41
	v_mul_f32_e32 v2, 0x45800000, v0
	v_cndmask_b32_e32 v0, v0, v2, vcc
	v_pk_mul_f32 v[2:3], v[0:1], v[86:87] op_sel_hi:[0,1]
	v_pk_mul_f32 v[2:3], v[8:9], v[2:3]
	v_cmp_gt_f32_e32 vcc, s83, v74
	v_cvt_pk_bf16_f32 v68, v2, v3
	v_pk_mul_f32 v[2:3], v[0:1], v[82:83] op_sel_hi:[0,1]
	v_pk_mul_f32 v[2:3], v[10:11], v[2:3]
	v_and_b32_e32 v97, 0xffff0000, v40
	v_cvt_pk_bf16_f32 v69, v2, v3
	v_pk_mul_f32 v[2:3], v[0:1], v[76:77] op_sel_hi:[0,1]
	v_pk_mul_f32 v[2:3], v[4:5], v[2:3]
	v_lshlrev_b32_e32 v76, 16, v63
	v_cvt_pk_bf16_f32 v70, v2, v3
	v_pk_mul_f32 v[2:3], v[0:1], v[72:73] op_sel_hi:[0,1]
	v_mul_f32_e32 v0, 0x4b800000, v74
	v_cndmask_b32_e32 v0, v74, v0, vcc
	v_rsq_f32_e32 v0, v0
	v_pk_mul_f32 v[2:3], v[6:7], v[2:3]
	v_and_b32_e32 v77, 0xffff0000, v63
	v_cvt_pk_bf16_f32 v71, v2, v3
	v_mul_f32_e32 v2, 0x45800000, v0
	v_cndmask_b32_e32 v0, v0, v2, vcc
	v_pk_mul_f32 v[2:3], v[0:1], v[102:103] op_sel_hi:[0,1]
	v_pk_mul_f32 v[2:3], v[8:9], v[2:3]
	ds_write_b128 v234, v[68:71]
	v_cvt_pk_bf16_f32 v68, v2, v3
	v_pk_mul_f32 v[2:3], v[0:1], v[98:99] op_sel_hi:[0,1]
	v_pk_mul_f32 v[2:3], v[10:11], v[2:3]
	v_lshlrev_b32_e32 v72, 16, v65
	v_cvt_pk_bf16_f32 v69, v2, v3
	v_pk_mul_f32 v[2:3], v[0:1], v[94:95] op_sel_hi:[0,1]
	v_pk_mul_f32 v[2:3], v[4:5], v[2:3]
	v_and_b32_e32 v73, 0xffff0000, v65
	v_cvt_pk_bf16_f32 v70, v2, v3
	v_pk_mul_f32 v[2:3], v[0:1], v[90:91] op_sel_hi:[0,1]
	v_pk_mul_f32 v[2:3], v[6:7], v[2:3]
	v_lshlrev_b32_e32 v74, 16, v64
	v_cvt_pk_bf16_f32 v71, v2, v3
	ds_write_b128 v235, v[68:71]
	v_lshlrev_b32_e32 v68, 16, v67
	v_and_b32_e32 v69, 0xffff0000, v67
	v_lshlrev_b32_e32 v70, 16, v66
	v_and_b32_e32 v71, 0xffff0000, v66
	v_pk_mul_f32 v[78:79], v[68:69], v[68:69]
	v_pk_mul_f32 v[80:81], v[70:71], v[70:71]
	v_pk_fma_f32 v[100:101], v[76:77], v[76:77], v[78:79]
	v_lshlrev_b32_e32 v78, 16, v62
	v_and_b32_e32 v79, 0xffff0000, v62
	v_pk_fma_f32 v[102:103], v[78:79], v[78:79], v[80:81]
	v_lshlrev_b32_e32 v80, 16, v61
	v_and_b32_e32 v81, 0xffff0000, v61
	v_pk_mul_f32 v[82:83], v[72:73], v[72:73]
	v_mul_f32_e32 v0, v96, v96
	v_pk_fma_f32 v[104:105], v[80:81], v[80:81], v[82:83]
	v_lshlrev_b32_e32 v82, 16, v60
	v_and_b32_e32 v83, 0xffff0000, v60
	v_pk_mul_f32 v[106:107], v[74:75], v[74:75]
	v_pk_mul_f32 v[94:95], v[92:93], v[92:93]
	v_pk_fma_f32 v[98:99], v[96:97], v[96:97], v[0:1] op_sel_hi:[1,1,0]
	v_pk_fma_f32 v[106:107], v[82:83], v[82:83], v[106:107]
	v_lshlrev_b32_e32 v88, 16, v42
	v_and_b32_e32 v89, 0xffff0000, v42
	v_mov_b32_e32 v108, v106
	v_mov_b32_e32 v109, v94
	v_mov_b32_e32 v98, v107
	v_pk_mul_f32 v[90:91], v[88:89], v[88:89]
	v_pk_add_f32 v[98:99], v[108:109], v[98:99]
	v_mov_b32_e32 v94, v104
	v_lshlrev_b32_e32 v2, 16, v43
	v_and_b32_e32 v3, 0xffff0000, v43
	v_pk_add_f32 v[94:95], v[94:95], v[98:99]
	v_pk_mov_b32 v[98:99], v[104:105], v[90:91] op_sel:[1,0]
	v_pk_mul_f32 v[86:87], v[2:3], v[2:3]
	v_pk_add_f32 v[94:95], v[98:99], v[94:95]
	v_mov_b32_e32 v90, v102
	v_pk_add_f32 v[90:91], v[90:91], v[94:95]
	v_pk_mov_b32 v[94:95], v[102:103], v[86:87] op_sel:[1,0]
	v_mov_b32_e32 v86, v100
	v_pk_add_f32 v[90:91], v[94:95], v[90:91]
	v_and_b32_e32 v0, 0xffff, v44
	v_pk_add_f32 v[86:87], v[86:87], v[90:91]
	ds_bpermute_b32 v91, v174, v87
	v_mov_b32_e32 v90, v101
	v_lshl_or_b32 v110, v48, 16, v0
	v_lshrrev_b32_e32 v0, 16, v44
	s_mov_b32 s0, 0xffff0000
	s_waitcnt lgkmcnt(0)
	v_pk_add_f32 v[86:87], v[90:91], v[86:87]
	v_and_or_b32 v111, v48, s0, v0
	v_and_b32_e32 v0, 0xffff, v45
	ds_bpermute_b32 v91, v175, v87
	ds_bpermute_b32 v90, v177, v86
	v_lshl_or_b32 v134, v49, 16, v0
	v_lshrrev_b32_e32 v0, 16, v45
	v_and_or_b32 v135, v49, s0, v0
	v_and_b32_e32 v0, 0xffff, v46
	v_lshl_or_b32 v136, v50, 16, v0
	v_lshrrev_b32_e32 v0, 16, v46
	v_and_or_b32 v137, v50, s0, v0
	v_and_b32_e32 v0, 0xffff, v47
	v_lshl_or_b32 v138, v51, 16, v0
	v_lshrrev_b32_e32 v0, 16, v47
	s_waitcnt lgkmcnt(0)
	v_pk_add_f32 v[86:87], v[86:87], v[90:91]
	v_and_or_b32 v139, v51, s0, v0
	v_and_b32_e32 v0, 0xffff, v52
	ds_bpermute_b32 v91, v176, v87
	ds_bpermute_b32 v90, v178, v86
	v_lshl_or_b32 v140, v56, 16, v0
	v_lshrrev_b32_e32 v0, 16, v52
	v_and_or_b32 v94, v56, s0, v0
	v_and_b32_e32 v0, 0xffff, v53
	v_lshl_or_b32 v95, v57, 16, v0
	v_lshrrev_b32_e32 v0, 16, v53
	v_and_or_b32 v98, v57, s0, v0
	v_and_b32_e32 v0, 0xffff, v54
	v_lshl_or_b32 v99, v58, 16, v0
	v_lshrrev_b32_e32 v0, 16, v54
	s_waitcnt lgkmcnt(0)
	v_pk_add_f32 v[86:87], v[86:87], v[90:91]
	v_and_or_b32 v100, v58, s0, v0
	v_and_b32_e32 v0, 0xffff, v55
	v_pk_fma_f32 v[84:85], v[86:87], s[24:25], v[84:85] op_sel_hi:[1,0,0]
	v_lshl_or_b32 v101, v59, 16, v0
	v_mul_f32_e32 v0, 0x4b800000, v85
	v_cmp_gt_f32_e32 vcc, s83, v85
	s_add_i32 s59, s58, s46
	s_cmpk_gt_i32 s59, 0xfff
	v_cndmask_b32_e32 v0, v85, v0, vcc
	v_rsq_f32_e32 v0, v0
	v_lshrrev_b32_e32 v85, 16, v55
	v_and_or_b32 v85, v59, s0, v85
	s_mov_b32 s0, 0x800000
	v_mul_f32_e32 v86, 0x45800000, v0
	v_cndmask_b32_e32 v0, v0, v86, vcc
	v_pk_mul_f32 v[86:87], v[0:1], v[96:97] op_sel_hi:[0,1]
	v_pk_mul_f32 v[90:91], v[0:1], v[92:93] op_sel_hi:[0,1]
	v_pk_mul_f32 v[88:89], v[0:1], v[88:89] op_sel_hi:[0,1]
	v_pk_mul_f32 v[2:3], v[0:1], v[2:3] op_sel_hi:[0,1]
	v_pk_mul_f32 v[86:87], v[8:9], v[86:87]
	v_pk_mul_f32 v[90:91], v[10:11], v[90:91]
	v_pk_mul_f32 v[88:89], v[4:5], v[88:89]
	v_pk_mul_f32 v[2:3], v[6:7], v[2:3]
	v_cvt_pk_bf16_f32 v86, v86, v87
	v_cvt_pk_bf16_f32 v87, v90, v91
	v_cvt_pk_bf16_f32 v88, v88, v89
	v_cvt_pk_bf16_f32 v89, v2, v3
	v_add_u32_e32 v0, 0x9000, v237
	ds_write_b128 v236, v[86:89]
	ds_write2_b32 v0, v110, v111 offset1:132
	v_add_u32_e32 v0, 0x9400, v237
	ds_write2_b32 v0, v134, v135 offset0:8 offset1:140
	v_add_u32_e32 v0, 0x9800, v237
	ds_write2_b32 v0, v136, v137 offset0:16 offset1:148
	v_add_u32_e32 v0, 0x9c00, v237
	ds_write2_b32 v0, v138, v139 offset0:24 offset1:156
	v_add_u32_e32 v0, 0x9000, v238
	ds_write2_b32 v0, v140, v94 offset1:132
	v_add_u32_e32 v0, 0x9400, v238
	ds_write2_b32 v0, v95, v98 offset0:8 offset1:140
	v_add_u32_e32 v0, 0x9800, v238
	s_cselect_b64 s[28:29], -1, 0
	v_cmp_gt_f32_e64 s[82:83], s0, v84
	ds_write2_b32 v0, v99, v100 offset0:16 offset1:148
	v_add_u32_e32 v0, 0x9c00, v238
	s_and_b64 vcc, exec, s[28:29]
	ds_write2_b32 v0, v101, v85 offset0:24 offset1:156
	s_cbranch_vccnz .LBB0_333
	s_and_b32 s0, 0xffff, s47
	s_and_b32 s25, s59, 0x7f
	s_ashr_i32 s24, s59, 11
	s_lshr_b32 s0, s25, s0
	s_and_b32 s25, s25, s56
	s_bfe_u32 s34, s59, 0x40007
	s_lshl_b32 s35, s25, 7
	s_lshl_b32 s25, s24, 4
	s_or_b32 s48, s25, s34
	s_ashr_i32 s49, s48, 31
	s_lshl_b64 s[48:49], s[48:49], 14
	s_lshl_b64 s[52:53], s[0:1], s99
	s_add_u32 s52, s52, s48
	s_addc_u32 s53, s53, s49
	s_add_i32 s25, s35, 0xffffff80
	v_mov_b32_e32 v30, v1
	v_mov_b32_e32 v31, v1
	v_add_u32_e32 v0, s25, v129
	v_mov_b32_e32 v28, v1
	v_mov_b32_e32 v29, v1
	v_mov_b64_e32 v[34:35], v[30:31]
	v_cmp_lt_i32_e32 vcc, -1, v0
	v_mov_b64_e32 v[32:33], v[28:29]
	s_and_saveexec_b64 s[54:55], vcc
	s_cbranch_execz .LBB0_321
	v_lshl_add_u64 v[2:3], s[52:53], 0, v[0:1]
	v_lshlrev_b64 v[2:3], 7, v[2:3]
	v_lshl_add_u64 v[2:3], v[122:123], 0, v[2:3]
	global_load_dwordx4 v[32:35], v[2:3], off
